# attention early-exit row-max butterfly also via DPP
# baseline (speedup 1.0000x reference)
.LBB0_259:
	v_add_u32_e32 v68, s92, v116
	v_add_u32_e32 v70, v68, v120
	ds_read_b128 v[48:51], v70
	ds_read_b128 v[52:55], v70 offset:4096
	ds_read_b128 v[56:59], v70 offset:8192
	ds_read_b128 v[94:97], v70 offset:12288
	v_add_u32_e32 v70, v68, v121
	v_add_u32_e32 v71, v68, v122
	ds_read_b128 v[174:177], v71 offset:12288
	v_add_u32_e32 v68, v68, v123
	ds_read_b128 v[178:181], v68 offset:12288
	s_waitcnt lgkmcnt(0)
	v_mfma_f32_16x16x32_bf16 v[52:55], v[52:55], v[0:3], 0
	v_mfma_f32_16x16x32_bf16 v[98:101], v[56:59], v[0:3], 0
	ds_read_b128 v[56:59], v70 offset:12288
	v_mfma_f32_16x16x32_bf16 v[94:97], v[94:97], v[0:3], 0
	s_waitcnt lgkmcnt(0)
	v_mfma_f32_16x16x32_bf16 v[56:59], v[56:59], v[4:7], v[94:97]
	s_nop 5
	ds_read_b128 v[94:97], v70 offset:8192
	ds_read_b128 v[182:185], v71 offset:8192
	ds_read_b128 v[186:189], v68 offset:8192
	v_mfma_f32_16x16x32_bf16 v[56:59], v[174:177], v[8:11], v[56:59]
	ds_read_b128 v[174:177], v70
	ds_read_b128 v[190:193], v70 offset:4096
	ds_read_b128 v[194:197], v71
	ds_read_b128 v[198:201], v71 offset:4096
	v_mfma_f32_16x16x32_bf16 v[56:59], v[178:181], v[12:15], v[56:59]
	ds_read_b128 v[178:181], v68
	ds_read_b128 v[202:205], v68 offset:4096
	s_waitcnt lgkmcnt(0)
	v_mfma_f32_16x16x32_bf16 v[94:97], v[94:97], v[4:7], v[98:101]
	s_nop 3
	v_exp_f32_e64 v70, -|v56|
	v_exp_f32_e64 v73, -|v57|
	v_max_f32_e32 v68, v56, v56
	v_mfma_f32_16x16x32_bf16 v[48:51], v[48:51], v[0:3], 0
	v_add_f32_e32 v70, 1.0, v70
	v_log_f32_e32 v70, v70
	v_max_f32_e32 v68, 0, v68
	v_mfma_f32_16x16x32_bf16 v[94:97], v[182:185], v[8:11], v[94:97]
	v_add_f32_e32 v68, v68, v70
	v_max_f32_e32 v70, v57, v57
	v_mfma_f32_16x16x32_bf16 v[52:55], v[190:193], v[4:7], v[52:55]
	v_max_f32_e32 v71, 0, v70
	v_add_f32_e32 v70, 1.0, v73
	v_max_f32_e32 v73, v58, v58
	v_mfma_f32_16x16x32_bf16 v[48:51], v[174:177], v[4:7], v[48:51]
	v_max_f32_e32 v193, 0, v73
	v_max_f32_e32 v73, v59, v59
	v_max_f32_e32 v183, 0, v73
	v_mfma_f32_16x16x32_bf16 v[174:177], v[186:189], v[12:15], v[94:97]
	v_log_f32_e32 v191, v70
	v_exp_f32_e64 v70, -|v58|
	v_mfma_f32_16x16x32_bf16 v[52:55], v[198:201], v[8:11], v[52:55]
	v_add_u32_e32 v198, s90, v159
	s_nop 3
	v_exp_f32_e64 v73, -|v174|
	v_exp_f32_e64 v94, -|v175|
	v_mfma_f32_16x16x32_bf16 v[52:55], v[202:205], v[12:15], v[52:55]
	v_exp_f32_e64 v96, -|v177|
	v_add_f32_e32 v73, 1.0, v73
	v_log_f32_e32 v190, v73
	v_max_f32_e32 v73, v175, v175
	v_max_f32_e32 v192, 0, v73
	v_add_f32_e32 v73, 1.0, v94
	v_exp_f32_e64 v94, -|v176|
	s_nop 0
	v_exp_f32_e64 v97, -|v52|
	v_add_f32_e32 v96, 1.0, v96
	v_mfma_f32_16x16x32_bf16 v[48:51], v[194:197], v[8:11], v[48:51]
	v_log_f32_e32 v194, v73
	v_max_f32_e32 v73, v176, v176
	v_log_f32_e32 v96, v96
	v_max_f32_e32 v182, 0, v73
	v_add_f32_e32 v73, 1.0, v94
	v_add_f32_e32 v97, 1.0, v97
	v_log_f32_e32 v94, v73
	v_max_f32_e32 v73, v177, v177
	v_log_f32_e32 v97, v97
	v_max_f32_e32 v73, 0, v73
	v_add_f32_e32 v185, v73, v96
	v_max_f32_e32 v73, v52, v52
	v_exp_f32_e64 v96, -|v54|
	v_max_f32_e32 v73, 0, v73
	v_add_f32_e32 v97, v73, v97
	v_exp_f32_e64 v73, -|v53|
	v_add_f32_e32 v96, 1.0, v96
	v_mfma_f32_16x16x32_bf16 v[48:51], v[178:181], v[12:15], v[48:51]
	v_log_f32_e32 v96, v96
	v_add_f32_e32 v73, 1.0, v73
	v_log_f32_e32 v181, v73
	v_max_f32_e32 v73, v54, v54
	v_max_f32_e32 v73, 0, v73
	v_add_f32_e32 v196, v73, v96
	s_nop 1
	v_exp_f32_e64 v96, -|v48|
	v_exp_f32_e64 v73, -|v55|
	v_exp_f32_e64 v100, -|v50|
	v_add_f32_e32 v70, 1.0, v70
	v_add_f32_e32 v96, 1.0, v96
	v_log_f32_e32 v96, v96
	v_add_f32_e32 v73, 1.0, v73
	v_log_f32_e32 v180, v73
	v_max_f32_e32 v73, v48, v48
	v_max_f32_e32 v73, 0, v73
	v_add_f32_e32 v73, v73, v96
	v_exp_f32_e64 v96, -|v49|
	v_max_f32_e32 v98, v53, v53
	v_log_f32_e32 v195, v70
	v_exp_f32_e64 v70, -|v59|
	v_add_f32_e32 v96, 1.0, v96
	v_log_f32_e32 v101, v96
	v_add_f32_e32 v96, 1.0, v100
	v_max_f32_e32 v179, 0, v98
	v_max_f32_e32 v98, v55, v55
	v_log_f32_e32 v96, v96
	v_max_f32_e32 v178, 0, v98
	v_max_f32_e32 v98, v49, v49
	v_exp_f32_e64 v100, -|v51|
	v_max_f32_e32 v99, 0, v98
	v_max_f32_e32 v98, v50, v50
	v_max_f32_e32 v98, 0, v98
	v_add_f32_e32 v70, 1.0, v70
	v_add_f32_e32 v197, v98, v96
	v_max_f32_e32 v96, v51, v51
	v_log_f32_e32 v95, v70
	v_max_f32_e32 v98, 0, v96
	v_add_f32_e32 v96, 1.0, v100
	v_cmp_lt_u32_e64 s[12:13], v198, v60
	v_max_f32_e32 v70, v174, v174
	v_log_f32_e32 v100, v96
	v_cndmask_b32_e64 v96, 0, -v73, s[12:13]
	v_or_b32_e32 v73, 48, v198
	v_max_f32_e32 v70, 0, v70
	v_or_b32_e32 v188, 33, v198
	v_or_b32_e32 v189, 32, v198
	v_or_b32_e32 v201, 49, v198
	v_cmp_lt_u32_e64 s[14:15], v73, v60
	v_or_b32_e32 v204, 50, v198
	v_pk_add_f32 v[70:71], v[70:71], v[190:191]
	v_cndmask_b32_e64 v184, 0, -v68, s[14:15]
	v_pk_add_f32 v[186:187], v[192:193], v[194:195]
	v_cmp_lt_u32_e64 s[16:17], v204, v60
	v_cmp_lt_u32_e32 vcc, v188, v61
	v_cmp_lt_u32_e64 s[18:19], v201, v61
	v_cmp_lt_u32_e64 s[8:9], v189, v60
	v_add_f32_e32 v73, 0, v184
	v_or_b32_e32 v202, 34, v198
	v_or_b32_e32 v203, 51, v198
	v_pk_add_f32 v[94:95], v[182:183], v[94:95]
	v_cndmask_b32_e64 v183, 0, -v187, s[16:17]
	v_cndmask_b32_e64 v182, 0, -v186, vcc
	v_cndmask_b32_e64 v187, 0, -v71, s[18:19]
	v_cndmask_b32_e64 v186, 0, -v70, s[8:9]
	v_pk_add_f32 v[70:71], v[186:187], v[72:73]
	v_cmp_lt_u32_e64 s[24:25], v203, v61
	v_cmp_lt_u32_e64 s[20:21], v202, v60
	v_pk_add_f32 v[70:71], v[182:183], v[70:71]
	v_cndmask_b32_e64 v189, 0, -v95, s[24:25]
	v_cndmask_b32_e64 v188, 0, -v94, s[20:21]
	v_pk_add_f32 v[70:71], v[188:189], v[70:71]
	ds_bpermute_b32 v95, v85, v71
	v_or_b32_e32 v68, 35, v198
	v_cmp_lt_u32_e64 s[10:11], v68, v61
	ds_bpermute_b32 v191, v87, v71
	v_add_f32_e32 v201, v176, v188
	v_cndmask_b32_e64 v94, 0, -v185, s[10:11]
	s_waitcnt lgkmcnt(0)
	v_pk_add_f32 v[70:71], v[94:95], v[70:71]
	ds_bpermute_b32 v190, v85, v70
	ds_bpermute_b32 v193, v87, v95
	ds_bpermute_b32 v192, v87, v70
	v_add_f32_e32 v185, v58, v183
	v_cndmask_b32_e64 v58, 0, v95, s[0:1]
	s_waitcnt lgkmcnt(0)
	ds_bpermute_b32 v68, v87, v190
	v_pk_add_f32 v[70:71], v[70:71], v[190:191]
	v_cndmask_b32_e64 v73, 0, v190, s[0:1]
	v_cndmask_b32_e64 v95, 0, v192, s[22:23]
	v_pk_add_f32 v[70:71], v[70:71], v[192:193]
	v_add_f32_e32 v73, v73, v95
	s_waitcnt lgkmcnt(0)
	v_cndmask_b32_e64 v95, 0, v68, s[4:5]
	v_pk_add_f32 v[194:195], v[70:71], v[68:69]
	v_cndmask_b32_e64 v68, 0, v191, s[22:23]
	v_add_f32_e32 v58, v58, v68
	v_cndmask_b32_e64 v68, 0, v193, s[4:5]
	v_mov_b32_e32 v70, v188
	v_add_f32_e32 v188, v58, v68
	v_mov_b32_e32 v58, v69
	v_pk_add_f32 v[58:59], v[58:59], v[188:189]
	v_add_f32_e32 v202, v177, v94
	v_pk_add_f32 v[176:177], v[72:73], v[94:95]
	v_mov_b32_e32 v71, v195
	v_add_f32_e32 v68, v58, v59
	v_pk_add_f32 v[70:71], v[70:71], v[176:177]
	v_add_f32_e32 v68, 0, v68
	v_add_f32_e32 v204, v175, v182
	v_mov_b32_e32 v94, v182
	v_mov_b32_e32 v95, v174
	v_mov_b32_e32 v174, v70
	v_mov_b32_e32 v175, v186
	v_exp_f32_e32 v177, v68
	v_mov_b32_e32 v68, v189
	v_mov_b32_e32 v69, v57
	v_mov_b32_e32 v73, v187
	v_pk_add_f32 v[94:95], v[94:95], v[174:175]
	v_pk_add_f32 v[68:69], v[68:69], v[72:73]
	v_pk_mov_b32 v[174:175], v[182:183], v[58:59] op_sel:[1,0]
	v_add_f32_e32 v186, v58, v185
	v_pk_add_f32 v[174:175], v[174:175], v[68:69]
	v_mov_b32_e32 v57, v187
	v_mov_b32_e32 v185, v174
	v_pk_add_f32 v[56:57], v[56:57], v[184:185]
	v_add_f32_e32 v59, v68, v186
	v_add_f32_e32 v56, v58, v56
	v_add_f32_e32 v56, v56, v57
	v_exp_f32_e32 v56, v56
	v_exp_f32_e32 v59, v59
	v_add_f32_e32 v68, v174, v175
	v_exp_f32_e32 v68, v68
	v_cndmask_b32_e64 v187, 0, v56, s[14:15]
	v_add_f32_e32 v56, v201, v71
	v_add_f32_e32 v56, v176, v56
	v_exp_f32_e32 v56, v56
	v_add_f32_e32 v57, v202, v71
	v_add_f32_e32 v57, 0, v57
	v_or_b32_e32 v58, 2, v198
	v_cndmask_b32_e64 v189, 0, v56, s[20:21]
	v_or_b32_e32 v56, 16, v198
	v_cndmask_b32_e64 v185, 0, v59, s[16:17]
	v_exp_f32_e32 v188, v57
	v_or_b32_e32 v57, 17, v198
	v_cmp_lt_u32_e64 s[16:17], v56, v60
	v_cmp_lt_u32_e64 s[14:15], v58, v60
	v_cndmask_b32_e64 v186, 0, v68, s[18:19]
	v_cndmask_b32_e64 v56, 0, -v97, s[16:17]
	v_cndmask_b32_e64 v58, 0, -v197, s[14:15]
	v_or_b32_e32 v68, 18, v198
	v_pk_add_f32 v[174:175], v[178:179], v[180:181]
	v_cmp_lt_u32_e64 s[20:21], v57, v61
	v_add_f32_e32 v59, 0, v56
	v_add_f32_e32 v191, v50, v58
	v_or_b32_e32 v50, 19, v198
	v_cmp_lt_u32_e64 s[18:19], v68, v60
	v_cndmask_b32_e64 v175, 0, -v175, s[20:21]
	v_cndmask_b32_e64 v184, 0, v177, s[24:25]
	v_cndmask_b32_e64 v68, 0, -v196, s[18:19]
	v_cmp_lt_u32_e64 s[24:25], v50, v61
	v_add_f32_e32 v50, v175, v59
	v_add_f32_e32 v50, v68, v50
	v_cndmask_b32_e64 v174, 0, -v174, s[24:25]
	v_add_f32_e32 v50, v174, v50
	ds_bpermute_b32 v57, v85, v50
	ds_bpermute_b32 v176, v87, v50
	v_mov_b32_e32 v73, v53
	v_mov_b32_e32 v181, v194
	v_mov_b32_e32 v183, v195
	s_waitcnt lgkmcnt(0)
	ds_bpermute_b32 v177, v87, v57
	v_add_f32_e32 v50, v50, v57
	v_add_f32_e32 v179, v50, v176
	v_cndmask_b32_e64 v50, 0, v57, s[0:1]
	v_cndmask_b32_e64 v53, 0, v176, s[22:23]
	v_add_f32_e32 v180, v50, v53
	s_waitcnt lgkmcnt(0)
	v_cndmask_b32_e64 v182, 0, v177, s[4:5]
	v_pk_add_f32 v[180:181], v[180:181], v[182:183]
	v_add_f32_e32 v69, v54, v68
	v_mov_b32_e32 v53, v180
	v_mov_b32_e32 v57, v181
	v_add_f32_e32 v59, v55, v174
	v_pk_add_f32 v[52:53], v[52:53], v[56:57]
	v_pk_add_f32 v[54:55], v[72:73], v[174:175]
	v_add_f32_e32 v50, v59, v53
	v_add_f32_e32 v56, v69, v53
	v_add_f32_e32 v50, 0, v50
	v_add_f32_e32 v56, v54, v56
	v_exp_f32_e32 v56, v56
	v_exp_f32_e32 v50, v50
	v_mov_b32_e32 v69, v53
	v_add_u32_e32 v199, 1, v198
	v_pk_add_f32 v[54:55], v[68:69], v[54:55]
	v_or_b32_e32 v97, 3, v198
	v_cndmask_b32_e64 v68, 0, v56, s[18:19]
	v_cndmask_b32_e64 v69, 0, v50, s[24:25]
	v_add_f32_e32 v50, v54, v55
	v_add_f32_e32 v55, v52, v53
	v_pk_add_f32 v[52:53], v[98:99], v[100:101]
	v_cmp_lt_u32_e64 s[18:19], v199, v61
	v_add_f32_e32 v200, 0, v96
	v_cmp_lt_u32_e64 s[24:25], v97, v61
	v_cndmask_b32_e64 v57, 0, -v53, s[18:19]
	v_exp_f32_e32 v50, v50
	v_cndmask_b32_e64 v56, 0, -v52, s[24:25]
	v_add_f32_e32 v52, v57, v200
	v_add_f32_e32 v52, v58, v52
	v_add_f32_e32 v182, v56, v52
	ds_bpermute_b32 v183, v85, v182
	v_add_f32_e32 v52, v175, v54
	ds_bpermute_b32 v192, v87, v182
	v_add_f32_e32 v52, v52, v55
	v_exp_f32_e32 v52, v52
	s_waitcnt lgkmcnt(0)
	ds_bpermute_b32 v193, v87, v183
	v_cndmask_b32_e64 v178, 0, v183, s[0:1]
	v_cndmask_b32_e64 v176, 0, v192, s[22:23]
	v_cndmask_b32_e64 v99, 0, v52, s[16:17]
	v_pk_add_f32 v[52:53], v[178:179], v[176:177]
	s_waitcnt lgkmcnt(0)
	v_cndmask_b32_e64 v180, 0, v193, s[4:5]
	v_pk_add_f32 v[52:53], v[52:53], v[180:181]
	v_mov_b32_e32 v73, v49
	v_mov_b32_e32 v49, v52
	v_mov_b32_e32 v97, v53
	v_pk_add_f32 v[48:49], v[48:49], v[96:97]
	v_cndmask_b32_e64 v98, 0, v50, s[20:21]
	v_add_f32_e32 v100, v51, v56
	v_pk_add_f32 v[50:51], v[72:73], v[56:57]
	v_mov_b32_e32 v59, v49
	v_pk_add_f32 v[54:55], v[58:59], v[50:51]
	v_add_f32_e32 v51, v100, v49
	v_add_f32_e32 v52, v191, v49
	v_add_f32_e32 v48, v48, v49
	v_add_f32_e32 v49, v57, v54
	v_add_f32_e32 v51, 0, v51
	v_add_f32_e32 v50, v50, v52
	v_add_f32_e32 v52, v54, v55
	v_add_f32_e32 v48, v49, v48
	v_exp_f32_e32 v51, v51
	v_exp_f32_e32 v50, v50
	v_exp_f32_e32 v52, v52
	v_exp_f32_e32 v48, v48
	v_bfe_u32 v59, v68, 16, 1
	v_cndmask_b32_e64 v49, 0, v50, s[14:15]
	v_cndmask_b32_e64 v50, 0, v51, s[24:25]
	v_cndmask_b32_e64 v51, 0, v52, s[18:19]
	v_cndmask_b32_e64 v48, 0, v48, s[12:13]
	v_add_u32_e32 v52, s92, v75
	v_bfe_u32 v56, v48, 16, 1
	v_bfe_u32 v57, v51, 16, 1
	v_bfe_u32 v73, v50, 16, 1
	v_bfe_u32 v96, v49, 16, 1
	v_add3_u32 v59, v68, v59, s84
	v_add3_u32 v68, v52, v124, v117
	v_add3_u32 v191, v52, v125, v117
	v_add3_u32 v97, v51, v57, s84
	v_add3_u32 v100, v48, v56, s84
	v_add3_u32 v101, v49, v96, s84
	v_add3_u32 v73, v50, v73, s84
	ds_read2st64_b64 v[48:51], v68 offset0:32 offset1:36
	ds_read2st64_b64 v[54:57], v191 offset0:32 offset1:36
	v_bfe_u32 v58, v69, 16, 1
	v_add3_u32 v58, v69, v58, s84
	v_cvt_pk_bf16_f32 v98, v99, v98
	s_waitcnt lgkmcnt(0)
	v_mov_b32_e32 v174, v48
	v_mov_b32_e32 v175, v49
	v_mov_b32_e32 v176, v54
	v_mov_b32_e32 v177, v55
	v_perm_b32 v96, v97, v100, s85
	v_perm_b32 v99, v58, v59, s85
	v_perm_b32 v97, v73, v101, s85
	ds_read2st64_b64 v[178:181], v68 offset0:40 offset1:44
	v_mov_b32_e32 v54, v50
	v_mfma_f32_16x16x32_bf16 v[16:19], v[174:177], v[96:99], v[16:19]
	ds_read2st64_b64 v[174:177], v191 offset0:40 offset1:44
	v_mov_b32_e32 v55, v51
	s_waitcnt lgkmcnt(0)
	v_mov_b32_e32 v48, v178
	v_mov_b32_e32 v49, v179
	v_add_f32_e32 v190, v204, v71
	v_mov_b32_e32 v50, v174
	v_mov_b32_e32 v51, v175
	v_mfma_f32_16x16x32_bf16 v[20:23], v[54:57], v[96:99], v[20:23]
	v_add_f32_e32 v54, v70, v190
	v_exp_f32_e32 v58, v54
	ds_read2st64_b64 v[54:57], v68 offset0:48 offset1:52
	v_mfma_f32_16x16x32_bf16 v[24:27], v[48:51], v[96:99], v[24:27]
	ds_read2st64_b64 v[48:51], v191 offset0:48 offset1:52
	v_mov_b32_e32 v174, v180
	v_mov_b32_e32 v175, v181
	s_waitcnt lgkmcnt(0)
	v_mov_b32_e32 v178, v54
	v_mov_b32_e32 v179, v55
	v_mov_b32_e32 v180, v48
	v_add_f32_e32 v48, v95, v71
	v_mov_b32_e32 v181, v49
	v_mfma_f32_16x16x32_bf16 v[32:35], v[174:177], v[96:99], v[32:35]
	v_add_f32_e32 v59, v94, v48
	ds_read2st64_b64 v[68:71], v68 offset0:56 offset1:60
	ds_read2st64_b64 v[174:177], v191 offset0:56 offset1:60
	v_mov_b32_e32 v48, v56
	v_mov_b32_e32 v49, v57
	v_mfma_f32_16x16x32_bf16 v[28:31], v[178:181], v[96:99], v[28:31]
	s_waitcnt lgkmcnt(0)
	v_mov_b32_e32 v54, v68
	v_mov_b32_e32 v55, v69
	v_mov_b32_e32 v56, v174
	v_mov_b32_e32 v57, v175
	v_mfma_f32_16x16x32_bf16 v[36:39], v[48:51], v[96:99], v[36:39]
	v_exp_f32_e32 v48, v59
	v_mov_b32_e32 v174, v70
	v_mov_b32_e32 v175, v71
	v_cndmask_b32_e64 v49, 0, v188, s[10:11]
	v_cndmask_b32_e32 v50, 0, v58, vcc
	v_cndmask_b32_e64 v48, 0, v48, s[8:9]
	v_mfma_f32_16x16x32_bf16 v[40:43], v[54:57], v[96:99], v[40:43]
	v_bfe_u32 v51, v48, 16, 1
	v_bfe_u32 v54, v50, 16, 1
	v_bfe_u32 v55, v49, 16, 1
	v_mfma_f32_16x16x32_bf16 v[44:47], v[174:177], v[96:99], v[44:47]
	v_bfe_u32 v56, v189, 16, 1
	v_add3_u32 v174, v52, v126, v117
	v_add3_u32 v52, v52, v127, v117
	v_add3_u32 v69, v50, v54, s84
	v_add3_u32 v70, v48, v51, s84
	v_add3_u32 v73, v189, v56, s84
	v_add3_u32 v95, v49, v55, s84
	ds_read2st64_b64 v[48:51], v174 offset0:32 offset1:36
	ds_read2st64_b64 v[54:57], v52 offset0:32 offset1:36
	v_perm_b32 v94, v69, v70, s85
	s_waitcnt lgkmcnt(0)
	v_mov_b32_e32 v68, v48
	v_mov_b32_e32 v69, v49
	v_mov_b32_e32 v70, v54
	v_mov_b32_e32 v71, v55
	v_perm_b32 v95, v95, v73, s85
	v_cvt_pk_bf16_f32 v96, v187, v186
	v_cvt_pk_bf16_f32 v97, v185, v184
	ds_read2st64_b64 v[98:101], v174 offset0:40 offset1:44
	v_mov_b32_e32 v54, v50
	v_mfma_f32_16x16x32_bf16 v[16:19], v[68:71], v[94:97], v[16:19]
	ds_read2st64_b64 v[68:71], v52 offset0:40 offset1:44
	v_mov_b32_e32 v55, v51
	s_waitcnt lgkmcnt(0)
	v_mov_b32_e32 v48, v98
	v_mov_b32_e32 v49, v99
	v_mfma_f32_16x16x32_bf16 v[20:23], v[54:57], v[94:97], v[20:23]
	v_mov_b32_e32 v50, v68
	v_mov_b32_e32 v51, v69
	v_add_f32_e32 v54, v182, v183
	v_add_f32_e32 v58, v54, v192
	ds_read2st64_b64 v[54:57], v174 offset0:48 offset1:52
	v_mov_b32_e32 v68, v100
	v_mov_b32_e32 v69, v101
	v_mfma_f32_16x16x32_bf16 v[24:27], v[48:51], v[94:97], v[24:27]
	ds_read2st64_b64 v[48:51], v52 offset0:48 offset1:52
	s_waitcnt lgkmcnt(0)
	v_mov_b32_e32 v98, v54
	v_add_f32_e32 v54, v58, v193
	v_mfma_f32_16x16x32_bf16 v[32:35], v[68:71], v[94:97], v[32:35]
	v_add_f32_e32 v69, v54, v53
	v_mov_b32_e32 v100, v48
	v_mov_b32_e32 v48, v56
	v_mov_b32_dpp v56, v69 quad_perm:[1,0,3,2] row_mask:0xf bank_mask:0xf
	v_mov_b32_e32 v101, v49
	v_mov_b32_e32 v49, v57
	v_mov_b32_e32 v99, v55
	s_waitcnt lgkmcnt(0)
	v_max_f32_e32 v56, v56, v56
	v_max_f32_e32 v68, v69, v56
	s_nop 1
	v_mov_b32_dpp v70, v68 quad_perm:[2,3,0,1] row_mask:0xf bank_mask:0xf
	v_mfma_f32_16x16x32_bf16 v[36:39], v[48:51], v[94:97], v[36:39]
	ds_read2st64_b64 v[48:51], v174 offset0:56 offset1:60
	ds_read2st64_b64 v[52:55], v52 offset0:56 offset1:60
	s_waitcnt lgkmcnt(0)
	v_mov_b32_e32 v56, v48
	v_max_f32_e32 v48, v70, v70
	v_max_f32_e32 v48, v68, v48
	v_mov_b32_e32 v57, v49
	s_nop 0
	v_mov_b32_dpp v49, v48 row_half_mirror row_mask:0xf bank_mask:0xf
	v_mov_b32_e32 v58, v52
	v_mov_b32_e32 v59, v53
	v_mov_b32_e32 v52, v50
	v_mov_b32_e32 v53, v51
	s_waitcnt lgkmcnt(0)
	v_max_f32_e32 v49, v49, v49
	v_max_f32_e32 v48, v48, v49
	s_nop 1
	v_mov_b32_dpp v49, v48 row_mirror row_mask:0xf bank_mask:0xf
	v_mfma_f32_16x16x32_bf16 v[28:31], v[98:101], v[94:97], v[28:31]
	v_mfma_f32_16x16x32_bf16 v[40:43], v[56:59], v[94:97], v[40:43]
	v_mfma_f32_16x16x32_bf16 v[44:47], v[52:55], v[94:97], v[44:47]
	s_and_saveexec_b64 s[8:9], s[6:7]
	s_cbranch_execz .LBB0_256
	s_waitcnt lgkmcnt(0)
	v_max_f32_e32 v49, v49, v49
	v_max_f32_e32 v48, v48, v48
	v_max_f32_e32 v48, v48, v49
	ds_write_b32 v119, v48
	s_branch .LBB0_256
